# GLA pass1 state tile stores: adjacent lanes exchanged with DPP so 32 two-byte global stores become 16 four-byte ones
# speedup vs baseline: 1.0049x; 1.0005x over previous
.LBB0_594:
	s_or_b64 exec, exec, s[2:3]
	v_and_b32_e32 v30, 31, v16
	v_ashrrev_i32_e32 v26, 7, v16
	v_bfe_u32 v17, v16, 5, 1
	v_lshl_or_b32 v0, v26, 5, v30
	s_movk_i32 s3, 0x90
	v_mul_lo_u32 v0, v0, s3
	v_lshlrev_b32_e32 v4, 4, v17
	v_readlane_b32 s2, v252, 12
	s_waitcnt lgkmcnt(0)
	s_barrier
	v_add3_u32 v31, s2, v0, v4
	ds_read_b128 v[0:3], v31
	v_readlane_b32 s2, v251, 5
	v_lshlrev_b32_e32 v35, 12, v26
	v_and_b32_e32 v34, 64, v16
	v_add_u32_e32 v32, s2, v4
	v_and_b32_e32 v4, 0x5f, v16
	v_mad_u32_u24 v33, v4, s3, v32
	ds_read_b128 v[4:7], v33
	s_waitcnt lgkmcnt(0)
	v_mfma_f32_32x32x16_bf16 v[0:15], v[0:3], v[4:7], 0
	ds_read_b128 v[18:21], v31 offset:32
	ds_read_b128 v[22:25], v33 offset:32
	ds_read_b128 v[26:29], v31 offset:96
	s_lshl_b64 s[0:1], s[0:1], 15
	s_add_u32 s0, s84, s0
	s_addc_u32 s1, s85, s1
	s_movk_i32 s2, 0x1000
	s_movk_i32 s40, 0x1000
	s_waitcnt lgkmcnt(0)
	v_mfma_f32_32x32x16_bf16 v[0:15], v[18:21], v[22:25], v[0:15]
	ds_read_b128 v[18:21], v31 offset:64
	ds_read_b128 v[22:25], v33 offset:64
	s_waitcnt lgkmcnt(0)
	v_mfma_f32_32x32x16_bf16 v[0:15], v[18:21], v[22:25], v[0:15]
	v_lshlrev_b32_e32 v20, 9, v17
	ds_read_b128 v[16:19], v33 offset:96
	v_or3_b32 v33, v20, v35, v30
	v_or_b32_e32 v24, v33, v34
	v_ashrrev_i32_e32 v25, 31, v24
	v_lshl_add_u64 v[20:21], v[24:25], 1, s[0:1]
	s_waitcnt lgkmcnt(0)
	v_mfma_f32_32x32x16_bf16 v[0:15], v[26:29], v[16:19], v[0:15]
	s_nop 11
	v_and_b32_e32 v164, 1, v207
	v_sub_u32_e32 v164, 0, v164
	v_and_b32_e32 v165, 0x6060606, v164
	v_xor_b32_e32 v165, 0x5040100, v165
	v_and_b32_e32 v163, 0xfe, v164
	v_add_co_u32_e32 v166, vcc, v163, v20
	s_nop 1
	v_addc_co_u32_e32 v167, vcc, 0, v21, vcc
	v_add_co_u32_e32 v178, vcc, 0x1000, v166
	s_nop 1
	v_addc_co_u32_e32 v179, vcc, 0, v167, vcc
	v_cvt_pk_bf16_f32 v168, v0, v1
	v_cvt_pk_bf16_f32 v169, v2, v3
	v_cvt_pk_bf16_f32 v170, v4, v5
	v_cvt_pk_bf16_f32 v171, v6, v7
	v_cvt_pk_bf16_f32 v172, v8, v9
	v_cvt_pk_bf16_f32 v173, v10, v11
	v_cvt_pk_bf16_f32 v174, v12, v13
	v_cvt_pk_bf16_f32 v175, v14, v15
	v_mov_b32_dpp v176, v168 quad_perm:[1,0,3,2] row_mask:0xf bank_mask:0xf
	v_perm_b32 v176, v176, v168, v165
	global_store_dword v[166:167], v176, off
	v_mov_b32_dpp v177, v169 quad_perm:[1,0,3,2] row_mask:0xf bank_mask:0xf
	v_perm_b32 v177, v177, v169, v165
	global_store_dword v[166:167], v177, off offset:512
	v_mov_b32_dpp v176, v170 quad_perm:[1,0,3,2] row_mask:0xf bank_mask:0xf
	v_perm_b32 v176, v176, v170, v165
	global_store_dword v[166:167], v176, off offset:2048
	v_mov_b32_dpp v177, v171 quad_perm:[1,0,3,2] row_mask:0xf bank_mask:0xf
	v_perm_b32 v177, v177, v171, v165
	global_store_dword v[166:167], v177, off offset:2560
	v_mov_b32_dpp v176, v172 quad_perm:[1,0,3,2] row_mask:0xf bank_mask:0xf
	v_perm_b32 v176, v176, v172, v165
	global_store_dword v[178:179], v176, off
	v_mov_b32_dpp v177, v173 quad_perm:[1,0,3,2] row_mask:0xf bank_mask:0xf
	v_perm_b32 v177, v177, v173, v165
	global_store_dword v[178:179], v177, off offset:512
	v_mov_b32_dpp v176, v174 quad_perm:[1,0,3,2] row_mask:0xf bank_mask:0xf
	v_perm_b32 v176, v176, v174, v165
	global_store_dword v[178:179], v176, off offset:2048
	v_mov_b32_dpp v177, v175 quad_perm:[1,0,3,2] row_mask:0xf bank_mask:0xf
	v_perm_b32 v177, v177, v175, v165
	global_store_dword v[178:179], v177, off offset:2560
	ds_read_b128 v[0:3], v31
	v_or3_b32 v4, v34, v30, 32
	v_mad_u32_u24 v25, v4, s3, v32
	ds_read_b128 v[4:7], v25
	s_waitcnt lgkmcnt(0)
	v_mfma_f32_32x32x16_bf16 v[0:15], v[0:3], v[4:7], 0
	ds_read_b128 v[16:19], v31 offset:32
	ds_read_b128 v[20:23], v25 offset:32
	s_waitcnt lgkmcnt(0)
	v_mfma_f32_32x32x16_bf16 v[0:15], v[16:19], v[20:23], v[0:15]
	ds_read_b128 v[16:19], v31 offset:64
	ds_read_b128 v[20:23], v25 offset:64
	s_waitcnt lgkmcnt(0)
	v_mfma_f32_32x32x16_bf16 v[0:15], v[16:19], v[20:23], v[0:15]
	ds_read_b128 v[16:19], v31 offset:96
	ds_read_b128 v[20:23], v25 offset:96
	v_ashrrev_i32_e32 v25, 31, v33
	v_lshl_add_u64 v[24:25], v[24:25], 1, s[0:1]
	s_waitcnt lgkmcnt(0)
	v_mfma_f32_32x32x16_bf16 v[0:15], v[16:19], v[20:23], v[0:15]
	s_nop 11
	v_add_co_u32_e32 v166, vcc, v163, v24
	s_nop 1
	v_addc_co_u32_e32 v167, vcc, 0, v25, vcc
	v_add_co_u32_e32 v178, vcc, 0x1000, v166
	s_nop 1
	v_addc_co_u32_e32 v179, vcc, 0, v167, vcc
	v_cvt_pk_bf16_f32 v168, v0, v1
	v_cvt_pk_bf16_f32 v169, v2, v3
	v_cvt_pk_bf16_f32 v170, v4, v5
	v_cvt_pk_bf16_f32 v171, v6, v7
	v_cvt_pk_bf16_f32 v172, v8, v9
	v_cvt_pk_bf16_f32 v173, v10, v11
	v_cvt_pk_bf16_f32 v174, v12, v13
	v_cvt_pk_bf16_f32 v175, v14, v15
	v_mov_b32_dpp v176, v168 quad_perm:[1,0,3,2] row_mask:0xf bank_mask:0xf
	v_perm_b32 v176, v176, v168, v165
	global_store_dword v[166:167], v176, off offset:64
	v_mov_b32_dpp v177, v169 quad_perm:[1,0,3,2] row_mask:0xf bank_mask:0xf
	v_perm_b32 v177, v177, v169, v165
	global_store_dword v[166:167], v177, off offset:576
	v_mov_b32_dpp v176, v170 quad_perm:[1,0,3,2] row_mask:0xf bank_mask:0xf
	v_perm_b32 v176, v176, v170, v165
	global_store_dword v[166:167], v176, off offset:2112
	v_mov_b32_dpp v177, v171 quad_perm:[1,0,3,2] row_mask:0xf bank_mask:0xf
	v_perm_b32 v177, v177, v171, v165
	global_store_dword v[166:167], v177, off offset:2624
	v_mov_b32_dpp v176, v172 quad_perm:[1,0,3,2] row_mask:0xf bank_mask:0xf
	v_perm_b32 v176, v176, v172, v165
	global_store_dword v[178:179], v176, off offset:64
	v_mov_b32_dpp v177, v173 quad_perm:[1,0,3,2] row_mask:0xf bank_mask:0xf
	v_perm_b32 v177, v177, v173, v165
	global_store_dword v[178:179], v177, off offset:576
	v_mov_b32_dpp v176, v174 quad_perm:[1,0,3,2] row_mask:0xf bank_mask:0xf
	v_perm_b32 v176, v176, v174, v165
	global_store_dword v[178:179], v176, off offset:2112
	v_mov_b32_dpp v177, v175 quad_perm:[1,0,3,2] row_mask:0xf bank_mask:0xf
	v_perm_b32 v177, v177, v175, v165
	global_store_dword v[178:179], v177, off offset:2624
	v_readlane_b32 s0, v251, 1
	s_add_i32 s8, s8, s0
	s_cmpk_gt_i32 s8, 0x83f
	v_readlane_b32 s1, v251, 2
	s_cbranch_scc1 .LBB0_617
